# phase0 weight transposes rewritten: wave-autonomous, no LDS/barriers, 52+ row loads in flight, 16B bf16 stores
# speedup vs baseline: 1.0319x; 1.0047x over previous
.LBB0_87:
	s_load_dwordx16 s[4:19], s[0:1], 0xc0
	s_cmpk_gt_i32 s54, 0x17ff
	s_waitcnt lgkmcnt(0)
	v_writelane_b32 v253, s4, 12
	s_nop 1
	v_writelane_b32 v253, s5, 13
	v_writelane_b32 v253, s6, 14
	v_writelane_b32 v253, s7, 15
	v_writelane_b32 v253, s8, 16
	v_writelane_b32 v253, s9, 17
	v_writelane_b32 v253, s10, 18
	v_writelane_b32 v253, s11, 19
	v_writelane_b32 v253, s12, 20
	v_writelane_b32 v253, s13, 21
	v_writelane_b32 v253, s14, 22
	v_writelane_b32 v253, s15, 23
	v_writelane_b32 v253, s16, 24
	v_writelane_b32 v253, s17, 25
	v_writelane_b32 v253, s18, 26
	v_writelane_b32 v253, s19, 27
	s_cbranch_scc1 .LBB0_143
	s_load_dwordx2 s[4:5], s[0:1], 0x40
	s_load_dwordx2 s[6:7], s[0:1], 0xe8
	s_load_dwordx4 s[8:11], s[0:1], 0xf0
	s_load_dwordx2 s[12:13], s[0:1], 0x110
	s_movk_i32 s15, 0x70
	s_add_i32 s14, s54, 3312
	s_movk_i32 s16, 0x17ff
	s_cmp_lt_u32 s54, 0x90
	s_cbranch_scc0 .Ltr_hi
	s_movk_i32 s15, 0x90
	s_mov_b32 s14, s54
	s_movk_i32 s16, 3455
.Ltr_hi:
	v_lshrrev_b32_e32 v139, 6, v211
	v_and_b32_e32 v136, 63, v211
	s_nop 1
	v_readfirstlane_b32 s17, v139
	s_nop 3
	s_mul_i32 s18, s17, s15
	s_add_i32 s14, s14, s18
	s_lshl_b32 s15, s15, 3
	v_lshlrev_b32_e32 v137, 2, v136
	v_cmp_gt_u32_e64 s[18:19], 32, v136
	s_waitcnt lgkmcnt(0)
.Ltr_loop:
	s_cmp_gt_i32 s14, s16
	s_cbranch_scc1 .Ltr_done
	s_movk_i32 s29, 64
	s_cmpk_lt_i32 s14, 0x580
	s_cbranch_scc1 .Ltr_A
	s_cmpk_lt_i32 s14, 0x780
	s_cbranch_scc1 .Ltr_B
	s_cmpk_lt_i32 s14, 0x1280
	s_cbranch_scc1 .Ltr_C
	s_add_i32 s30, s14, 0xffffed80
	s_cmpk_ge_i32 s30, 0x2c0
	s_cselect_b32 s31, 1, 0
	s_mul_i32 s34, s31, 0x2c0
	s_sub_i32 s30, s30, s34
	s_mul_i32 s35, s30, 0x5d2
	s_lshr_b32 s35, s35, 16
	s_mul_i32 s34, s35, 44
	s_sub_i32 s36, s30, s34
	s_mul_i32 s37, s31, 0xb00000
	s_lshl_b32 s38, s36, 18
	s_add_u32 s37, s37, s38
	s_add_u32 s20, s10, s37
	s_addc_u32 s21, s11, 0
	s_movk_i32 s22, 0x1000
	s_lshl_b32 s27, s35, 8
	s_mov_b32 s28, s27
	s_mul_i32 s37, s31, 0x580000
	s_mul_i32 s38, s35, 0x58000
	s_add_u32 s37, s37, s38
	s_lshl_b32 s38, s36, 7
	s_add_u32 s37, s37, s38
	s_add_u32 s37, s37, 0x2500000
	s_add_u32 s24, s12, s37
	s_addc_u32 s25, s13, 0
	s_movk_i32 s26, 0x1600
	s_branch .Ltr_go
.Ltr_B:
	s_add_i32 s30, s14, 0xfffffa80
	s_lshr_b32 s31, s30, 8
	s_and_b32 s30, s30, 0xff
	s_lshr_b32 s35, s30, 4
	s_and_b32 s36, s30, 15
	s_lshl_b32 s37, s31, 22
	s_lshl_b32 s38, s36, 18
	s_add_u32 s37, s37, s38
	s_add_u32 s20, s6, s37
	s_addc_u32 s21, s7, 0
	s_movk_i32 s22, 0x1000
	s_lshl_b32 s27, s35, 8
	s_mov_b32 s28, s27
	s_lshl_b32 s37, s31, 21
	s_lshl_b32 s38, s35, 17
	s_add_u32 s37, s37, s38
	s_lshl_b32 s38, s36, 7
	s_add_u32 s37, s37, s38
	s_add_u32 s37, s37, 0xb00000
	s_add_u32 s24, s12, s37
	s_addc_u32 s25, s13, 0
	s_movk_i32 s26, 0x800
	s_branch .Ltr_go
.Ltr_C:
	s_add_i32 s30, s14, 0xfffff880
	s_cmpk_ge_i32 s30, 0x580
	s_cselect_b32 s31, 1, 0
	s_mul_i32 s34, s31, 0x580
	s_sub_i32 s30, s30, s34
	s_lshr_b32 s35, s30, 4
	s_and_b32 s36, s30, 15
	s_lshr_b32 s39, s35, 2
	s_and_b32 s40, s35, 3
	s_lshl_b32 s41, s39, 7
	s_lshl_b32 s42, s40, 6
	s_add_i32 s41, s41, s42
	s_add_i32 s42, s41, 0xa80
	s_cmp_lt_u32 s40, 2
	s_cselect_b32 s41, s41, s42
	s_lshl_b32 s27, s41, 2
	s_mov_b32 s28, s27
	s_mul_i32 s37, s31, 0x1600000
	s_mul_i32 s38, s36, 0x160000
	s_add_u32 s37, s37, s38
	s_add_u32 s20, s8, s37
	s_addc_u32 s21, s9, 0
	s_movk_i32 s22, 0x5800
	s_mul_i32 s37, s31, 0xb00000
	s_lshl_b32 s38, s35, 17
	s_add_u32 s37, s37, s38
	s_lshl_b32 s38, s36, 7
	s_add_u32 s37, s37, s38
	s_add_u32 s37, s37, 0xf00000
	s_add_u32 s24, s12, s37
	s_addc_u32 s25, s13, 0
	s_movk_i32 s26, 0x800
	s_branch .Ltr_go
.Ltr_A:
	s_cmpk_ge_i32 s14, 0x2c0
	s_cselect_b32 s31, 1, 0
	s_mul_i32 s34, s31, 0x2c0
	s_sub_i32 s30, s14, s34
	s_lshr_b32 s35, s30, 4
	s_and_b32 s36, s30, 15
	s_lshr_b32 s39, s35, 2
	s_and_b32 s40, s35, 3
	s_lshl_b32 s41, s35, 6
	s_add_i32 s42, s41, 32
	s_cmp_lt_u32 s39, 5
	s_cbranch_scc1 .Ltr_A_cols
	s_cmp_eq_u32 s39, 7
	s_cbranch_scc1 .Ltr_A_m96
	s_cmp_eq_u32 s39, 8
	s_cbranch_scc1 .Ltr_A_m96
	s_add_i32 s43, s39, -5
	s_lshl_b32 s43, s43, 8
	s_addk_i32 s43, 0x4a0
	s_and_b32 s44, s40, 1
	s_lshl_b32 s44, s44, 7
	s_add_i32 s43, s43, s44
	s_lshr_b32 s44, s40, 1
	s_lshl_b32 s44, s44, 5
	s_add_i32 s41, s43, s44
	s_add_i32 s42, s41, 64
	s_branch .Ltr_A_cols
.Ltr_A_m96:
	s_add_i32 s41, s41, -96
	s_add_i32 s42, s41, 32
.Ltr_A_cols:
	s_lshl_b32 s27, s41, 2
	s_lshl_b32 s28, s42, 2
	s_add_i32 s28, s28, 0xffffff80
	s_cmp_lg_u32 s39, 4
	s_cbranch_scc1 .Ltr_A_nv
	s_cmp_lt_u32 s40, 2
	s_cbranch_scc1 .Ltr_A_nv
	s_movk_i32 s29, 32
	s_cmp_eq_u32 s40, 2
	s_cbranch_scc1 .Ltr_A_nv
	s_movk_i32 s29, 0
.Ltr_A_nv:
	s_mul_i32 s37, s31, 0xaa0000
	s_mul_i32 s38, s36, 0xaa000
	s_add_u32 s37, s37, s38
	s_add_u32 s20, s4, s37
	s_addc_u32 s21, s5, 0
	s_movk_i32 s22, 0x2a80
	s_mul_i32 s37, s31, 0x580000
	s_lshl_b32 s38, s35, 17
	s_add_u32 s37, s37, s38
	s_lshl_b32 s38, s36, 7
	s_add_u32 s37, s37, s38
	s_add_u32 s24, s12, s37
	s_addc_u32 s25, s13, 0
	s_movk_i32 s26, 0x800
.Ltr_go:
	v_add_u32_e32 v138, s27, v137
	v_add_u32_e32 v139, s28, v137
	v_cndmask_b32_e64 v138, v139, v138, s[18:19]
	v_mul_lo_u32 v140, v136, s26
	s_cmpk_eq_i32 s29, 64
	s_cbranch_scc1 .Ltr_ld
	v_mov_b32_e32 v40, 0
	v_mov_b32_e32 v41, 0
	v_mov_b32_e32 v42, 0
	v_mov_b32_e32 v43, 0
	v_mov_b32_e32 v44, 0
	v_mov_b32_e32 v45, 0
	v_mov_b32_e32 v46, 0
	v_mov_b32_e32 v47, 0
	v_mov_b32_e32 v48, 0
	v_mov_b32_e32 v49, 0
	v_mov_b32_e32 v50, 0
	v_mov_b32_e32 v51, 0
	v_mov_b32_e32 v52, 0
	v_mov_b32_e32 v53, 0
	v_mov_b32_e32 v54, 0
	v_mov_b32_e32 v55, 0
	v_mov_b32_e32 v56, 0
	v_mov_b32_e32 v57, 0
	v_mov_b32_e32 v58, 0
	v_mov_b32_e32 v59, 0
	v_mov_b32_e32 v60, 0
	v_mov_b32_e32 v61, 0
	v_mov_b32_e32 v62, 0
	v_mov_b32_e32 v63, 0
	v_mov_b32_e32 v64, 0
	v_mov_b32_e32 v65, 0
	v_mov_b32_e32 v66, 0
	v_mov_b32_e32 v67, 0
	v_mov_b32_e32 v68, 0
	v_mov_b32_e32 v69, 0
	v_mov_b32_e32 v70, 0
	v_mov_b32_e32 v71, 0
	v_mov_b32_e32 v72, 0
	v_mov_b32_e32 v73, 0
	v_mov_b32_e32 v74, 0
	v_mov_b32_e32 v75, 0
	v_mov_b32_e32 v76, 0
	v_mov_b32_e32 v77, 0
	v_mov_b32_e32 v78, 0
	v_mov_b32_e32 v79, 0
	v_mov_b32_e32 v80, 0
	v_mov_b32_e32 v81, 0
	v_mov_b32_e32 v82, 0
	v_mov_b32_e32 v83, 0
	v_mov_b32_e32 v84, 0
	v_mov_b32_e32 v85, 0
	v_mov_b32_e32 v86, 0
	v_mov_b32_e32 v87, 0
	v_mov_b32_e32 v88, 0
	v_mov_b32_e32 v89, 0
	v_mov_b32_e32 v90, 0
	v_mov_b32_e32 v91, 0
	v_mov_b32_e32 v92, 0
	v_mov_b32_e32 v93, 0
	v_mov_b32_e32 v94, 0
	v_mov_b32_e32 v95, 0
	v_mov_b32_e32 v96, 0
	v_mov_b32_e32 v97, 0
	v_mov_b32_e32 v98, 0
	v_mov_b32_e32 v99, 0
	v_mov_b32_e32 v100, 0
	v_mov_b32_e32 v101, 0
	v_mov_b32_e32 v102, 0
	v_mov_b32_e32 v103, 0
	s_cmpk_eq_i32 s29, 0
	s_cbranch_scc1 .Ltr_cv
	s_mov_b64 exec, s[18:19]
.Ltr_ld:
	global_load_dword v40, v138, s[20:21]
	s_add_u32 s20, s20, s22
	s_addc_u32 s21, s21, 0
	global_load_dword v41, v138, s[20:21]
	s_add_u32 s20, s20, s22
	s_addc_u32 s21, s21, 0
	global_load_dword v42, v138, s[20:21]
	s_add_u32 s20, s20, s22
	s_addc_u32 s21, s21, 0
	global_load_dword v43, v138, s[20:21]
	s_add_u32 s20, s20, s22
	s_addc_u32 s21, s21, 0
	global_load_dword v44, v138, s[20:21]
	s_add_u32 s20, s20, s22
	s_addc_u32 s21, s21, 0
	global_load_dword v45, v138, s[20:21]
	s_add_u32 s20, s20, s22
	s_addc_u32 s21, s21, 0
	global_load_dword v46, v138, s[20:21]
	s_add_u32 s20, s20, s22
	s_addc_u32 s21, s21, 0
	global_load_dword v47, v138, s[20:21]
	s_add_u32 s20, s20, s22
	s_addc_u32 s21, s21, 0
	global_load_dword v48, v138, s[20:21]
	s_add_u32 s20, s20, s22
	s_addc_u32 s21, s21, 0
	global_load_dword v49, v138, s[20:21]
	s_add_u32 s20, s20, s22
	s_addc_u32 s21, s21, 0
	global_load_dword v50, v138, s[20:21]
	s_add_u32 s20, s20, s22
	s_addc_u32 s21, s21, 0
	global_load_dword v51, v138, s[20:21]
	s_add_u32 s20, s20, s22
	s_addc_u32 s21, s21, 0
	global_load_dword v52, v138, s[20:21]
	s_add_u32 s20, s20, s22
	s_addc_u32 s21, s21, 0
	global_load_dword v53, v138, s[20:21]
	s_add_u32 s20, s20, s22
	s_addc_u32 s21, s21, 0
	global_load_dword v54, v138, s[20:21]
	s_add_u32 s20, s20, s22
	s_addc_u32 s21, s21, 0
	global_load_dword v55, v138, s[20:21]
	s_add_u32 s20, s20, s22
	s_addc_u32 s21, s21, 0
	global_load_dword v56, v138, s[20:21]
	s_add_u32 s20, s20, s22
	s_addc_u32 s21, s21, 0
	global_load_dword v57, v138, s[20:21]
	s_add_u32 s20, s20, s22
	s_addc_u32 s21, s21, 0
	global_load_dword v58, v138, s[20:21]
	s_add_u32 s20, s20, s22
	s_addc_u32 s21, s21, 0
	global_load_dword v59, v138, s[20:21]
	s_add_u32 s20, s20, s22
	s_addc_u32 s21, s21, 0
	global_load_dword v60, v138, s[20:21]
	s_add_u32 s20, s20, s22
	s_addc_u32 s21, s21, 0
	global_load_dword v61, v138, s[20:21]
	s_add_u32 s20, s20, s22
	s_addc_u32 s21, s21, 0
	global_load_dword v62, v138, s[20:21]
	s_add_u32 s20, s20, s22
	s_addc_u32 s21, s21, 0
	global_load_dword v63, v138, s[20:21]
	s_add_u32 s20, s20, s22
	s_addc_u32 s21, s21, 0
	global_load_dword v64, v138, s[20:21]
	s_add_u32 s20, s20, s22
	s_addc_u32 s21, s21, 0
	global_load_dword v65, v138, s[20:21]
	s_add_u32 s20, s20, s22
	s_addc_u32 s21, s21, 0
	global_load_dword v66, v138, s[20:21]
	s_add_u32 s20, s20, s22
	s_addc_u32 s21, s21, 0
	global_load_dword v67, v138, s[20:21]
	s_add_u32 s20, s20, s22
	s_addc_u32 s21, s21, 0
	global_load_dword v68, v138, s[20:21]
	s_add_u32 s20, s20, s22
	s_addc_u32 s21, s21, 0
	global_load_dword v69, v138, s[20:21]
	s_add_u32 s20, s20, s22
	s_addc_u32 s21, s21, 0
	global_load_dword v70, v138, s[20:21]
	s_add_u32 s20, s20, s22
	s_addc_u32 s21, s21, 0
	global_load_dword v71, v138, s[20:21]
	s_add_u32 s20, s20, s22
	s_addc_u32 s21, s21, 0
	global_load_dword v72, v138, s[20:21]
	s_add_u32 s20, s20, s22
	s_addc_u32 s21, s21, 0
	global_load_dword v73, v138, s[20:21]
	s_add_u32 s20, s20, s22
	s_addc_u32 s21, s21, 0
	global_load_dword v74, v138, s[20:21]
	s_add_u32 s20, s20, s22
	s_addc_u32 s21, s21, 0
	global_load_dword v75, v138, s[20:21]
	s_add_u32 s20, s20, s22
	s_addc_u32 s21, s21, 0
	global_load_dword v76, v138, s[20:21]
	s_add_u32 s20, s20, s22
	s_addc_u32 s21, s21, 0
	global_load_dword v77, v138, s[20:21]
	s_add_u32 s20, s20, s22
	s_addc_u32 s21, s21, 0
	global_load_dword v78, v138, s[20:21]
	s_add_u32 s20, s20, s22
	s_addc_u32 s21, s21, 0
	global_load_dword v79, v138, s[20:21]
	s_add_u32 s20, s20, s22
	s_addc_u32 s21, s21, 0
	global_load_dword v80, v138, s[20:21]
	s_add_u32 s20, s20, s22
	s_addc_u32 s21, s21, 0
	global_load_dword v81, v138, s[20:21]
	s_add_u32 s20, s20, s22
	s_addc_u32 s21, s21, 0
	global_load_dword v82, v138, s[20:21]
	s_add_u32 s20, s20, s22
	s_addc_u32 s21, s21, 0
	global_load_dword v83, v138, s[20:21]
	s_add_u32 s20, s20, s22
	s_addc_u32 s21, s21, 0
	global_load_dword v84, v138, s[20:21]
	s_add_u32 s20, s20, s22
	s_addc_u32 s21, s21, 0
	global_load_dword v85, v138, s[20:21]
	s_add_u32 s20, s20, s22
	s_addc_u32 s21, s21, 0
	global_load_dword v86, v138, s[20:21]
	s_add_u32 s20, s20, s22
	s_addc_u32 s21, s21, 0
	global_load_dword v87, v138, s[20:21]
	s_add_u32 s20, s20, s22
	s_addc_u32 s21, s21, 0
	global_load_dword v88, v138, s[20:21]
	s_add_u32 s20, s20, s22
	s_addc_u32 s21, s21, 0
	global_load_dword v89, v138, s[20:21]
	s_add_u32 s20, s20, s22
	s_addc_u32 s21, s21, 0
	global_load_dword v90, v138, s[20:21]
	s_add_u32 s20, s20, s22
	s_addc_u32 s21, s21, 0
	global_load_dword v91, v138, s[20:21]
	s_add_u32 s20, s20, s22
	s_addc_u32 s21, s21, 0
	s_waitcnt vmcnt(44)
	global_load_dword v92, v138, s[20:21]
	s_add_u32 s20, s20, s22
	s_addc_u32 s21, s21, 0
	global_load_dword v93, v138, s[20:21]
	s_add_u32 s20, s20, s22
	s_addc_u32 s21, s21, 0
	global_load_dword v94, v138, s[20:21]
	s_add_u32 s20, s20, s22
	s_addc_u32 s21, s21, 0
	global_load_dword v95, v138, s[20:21]
	s_add_u32 s20, s20, s22
	s_addc_u32 s21, s21, 0
	global_load_dword v96, v138, s[20:21]
	s_add_u32 s20, s20, s22
	s_addc_u32 s21, s21, 0
	global_load_dword v97, v138, s[20:21]
	s_add_u32 s20, s20, s22
	s_addc_u32 s21, s21, 0
	global_load_dword v98, v138, s[20:21]
	s_add_u32 s20, s20, s22
	s_addc_u32 s21, s21, 0
	global_load_dword v99, v138, s[20:21]
	s_add_u32 s20, s20, s22
	s_addc_u32 s21, s21, 0
	global_load_dword v100, v138, s[20:21]
	s_add_u32 s20, s20, s22
	s_addc_u32 s21, s21, 0
	global_load_dword v101, v138, s[20:21]
	s_add_u32 s20, s20, s22
	s_addc_u32 s21, s21, 0
	global_load_dword v102, v138, s[20:21]
	s_add_u32 s20, s20, s22
	s_addc_u32 s21, s21, 0
	global_load_dword v103, v138, s[20:21]
	s_mov_b64 exec, -1
.Ltr_cv:
	s_waitcnt vmcnt(56)
	v_cvt_pk_bf16_f32 v104, v40, v41
	v_cvt_pk_bf16_f32 v105, v42, v43
	v_cvt_pk_bf16_f32 v106, v44, v45
	v_cvt_pk_bf16_f32 v107, v46, v47
	global_store_dwordx4 v140, v[104:107], s[24:25]
	s_waitcnt vmcnt(49)
	v_cvt_pk_bf16_f32 v108, v48, v49
	v_cvt_pk_bf16_f32 v109, v50, v51
	v_cvt_pk_bf16_f32 v110, v52, v53
	v_cvt_pk_bf16_f32 v111, v54, v55
	global_store_dwordx4 v140, v[108:111], s[24:25] offset:16
	s_waitcnt vmcnt(42)
	v_cvt_pk_bf16_f32 v112, v56, v57
	v_cvt_pk_bf16_f32 v113, v58, v59
	v_cvt_pk_bf16_f32 v114, v60, v61
	v_cvt_pk_bf16_f32 v115, v62, v63
	global_store_dwordx4 v140, v[112:115], s[24:25] offset:32
	s_waitcnt vmcnt(35)
	v_cvt_pk_bf16_f32 v116, v64, v65
	v_cvt_pk_bf16_f32 v117, v66, v67
	v_cvt_pk_bf16_f32 v118, v68, v69
	v_cvt_pk_bf16_f32 v119, v70, v71
	global_store_dwordx4 v140, v[116:119], s[24:25] offset:48
	s_waitcnt vmcnt(28)
	v_cvt_pk_bf16_f32 v120, v72, v73
	v_cvt_pk_bf16_f32 v121, v74, v75
	v_cvt_pk_bf16_f32 v122, v76, v77
	v_cvt_pk_bf16_f32 v123, v78, v79
	global_store_dwordx4 v140, v[120:123], s[24:25] offset:64
	s_waitcnt vmcnt(21)
	v_cvt_pk_bf16_f32 v124, v80, v81
	v_cvt_pk_bf16_f32 v125, v82, v83
	v_cvt_pk_bf16_f32 v126, v84, v85
	v_cvt_pk_bf16_f32 v127, v86, v87
	global_store_dwordx4 v140, v[124:127], s[24:25] offset:80
	s_waitcnt vmcnt(14)
	v_cvt_pk_bf16_f32 v128, v88, v89
	v_cvt_pk_bf16_f32 v129, v90, v91
	v_cvt_pk_bf16_f32 v130, v92, v93
	v_cvt_pk_bf16_f32 v131, v94, v95
	global_store_dwordx4 v140, v[128:131], s[24:25] offset:96
	s_waitcnt vmcnt(7)
	v_cvt_pk_bf16_f32 v132, v96, v97
	v_cvt_pk_bf16_f32 v133, v98, v99
	v_cvt_pk_bf16_f32 v134, v100, v101
	v_cvt_pk_bf16_f32 v135, v102, v103
	global_store_dwordx4 v140, v[132:135], s[24:25] offset:112
	s_add_i32 s14, s14, s15
	s_branch .Ltr_loop
.Ltr_done:
	s_mov_b64 exec, -1
